# grid barrier: non-leader workgroups poll the top-level generation word directly
# speedup vs baseline: 1.0030x; 1.0030x over previous
; __device__ __forceinline__ unsigned xb_ld(unsigned* p)              { return __hip_atomic_load(p, __ATOMIC_RELAXED, __HIP_MEMORY_SCOPE_AGENT); }
; __device__ __forceinline__ unsigned xb_add(unsigned* p, unsigned v) { return __hip_atomic_fetch_add(p, v, __ATOMIC_RELAXED, __HIP_MEMORY_SCOPE_AGENT); }
; #define XB_SPIN(cond, bar) do { unsigned _sp = 0; while (cond) { __builtin_amdgcn_s_sleep(1); \
;     if ((++_sp & 255u) == 0u) { if (xb_ld(&(bar)[XB_TMO])) break; if (_sp > XB_SPIN_CAP) { atomicAdd(&(bar)[XB_TMO], 1u); break; } } } } while (0)
; __device__ __forceinline__ void xcd_barrier(const XcdBarrier& b) {
;     ...
;         const unsigned old = xb_add(&bar[XB_XSUB(b.x)], 1u);
;         const unsigned gen = old / nloc;
;         if (old + 1u == (gen + 1u) * nloc) {
;             __builtin_amdgcn_fence(__ATOMIC_RELEASE, "agent");
;             asm volatile("s_waitcnt vmcnt(0)" ::: "memory");
;             const unsigned og = xb_add(&bar[XB_TOP], 1u);
;             const unsigned tg = og / nx;
;             if (og + 1u == (tg + 1u) * nx) xb_add(&bar[XB_TOPGEN], 1u);
;             else XB_SPIN(xb_ld(&bar[XB_TOPGEN]) == tg, bar);
;             __builtin_amdgcn_fence(__ATOMIC_ACQUIRE, "agent");
;             xb_add(&bar[XB_XGEN(b.x)], 1u);
;             asm volatile("s_waitcnt vmcnt(0)" ::: "memory");
;         } else {
;             XB_SPIN(xb_ld(&bar[XB_XGEN(b.x)]) == gen, bar);
;             __builtin_amdgcn_fence(__ATOMIC_ACQUIRE, "agent");
;             asm volatile("s_waitcnt vmcnt(0)" ::: "memory");
;         }
.LBB0_358:
	s_or_b64 exec, exec, s[10:11]
	v_cvt_f32_u32_e32 v6, v4
	s_waitcnt vmcnt(0)
	v_readfirstlane_b32 s3, v5
	v_sub_u32_e32 v5, 0, v4
	v_rcp_iflag_f32_e32 v6, v6
	v_add_u32_e32 v7, s3, v3
	v_mul_f32_e32 v6, 0x4f7ffffe, v6
	v_cvt_u32_f32_e32 v6, v6
	v_mul_lo_u32 v3, v5, v6
	v_mul_hi_u32 v3, v6, v3
	v_add_u32_e32 v3, v6, v3
	v_mul_hi_u32 v3, v7, v3
	v_mul_lo_u32 v5, v3, v4
	v_sub_u32_e32 v5, v7, v5
	v_add_u32_e32 v6, 1, v3
	v_cmp_ge_u32_e32 vcc, v5, v4
	s_nop 1
	v_cndmask_b32_e32 v3, v3, v6, vcc
	v_sub_u32_e32 v6, v5, v4
	v_cndmask_b32_e32 v5, v5, v6, vcc
	v_add_u32_e32 v6, 1, v3
	v_cmp_ge_u32_e32 vcc, v5, v4
	v_add_u32_e32 v5, 1, v7
	s_nop 0
	v_cndmask_b32_e32 v3, v3, v6, vcc
	v_mul_lo_u32 v6, v4, v3
	v_add_u32_e32 v4, v6, v4
	v_cmp_ne_u32_e32 vcc, v5, v4
	s_and_saveexec_b64 s[4:5], vcc
	s_xor_b64 s[8:9], exec, s[4:5]
	s_cbranch_execz .LBB0_372
	s_waitcnt lgkmcnt(0)
	v_mov_b32_e32 v2, 0x7500
	global_load_dword v2, v2, s[94:95] sc1
	s_add_u32 s16, s94, 0x7500
	s_addc_u32 s17, s95, 0
	s_waitcnt vmcnt(0)
	v_cmp_gt_u32_e32 vcc, 1, v2
	s_and_saveexec_b64 s[10:11], vcc
	s_cbranch_execz .LBB0_371
	s_add_u32 s14, s94, 0x4200
	s_addc_u32 s15, s95, 0
	s_mov_b32 s3, 1
	s_mov_b64 s[18:19], 0
	v_mov_b32_e32 v2, 0
	s_branch .LBB0_362

; __device__ __forceinline__ unsigned xb_ld(unsigned* p)              { return __hip_atomic_load(p, __ATOMIC_RELAXED, __HIP_MEMORY_SCOPE_AGENT); }
; __device__ __forceinline__ unsigned xb_add(unsigned* p, unsigned v) { return __hip_atomic_fetch_add(p, v, __ATOMIC_RELAXED, __HIP_MEMORY_SCOPE_AGENT); }
; #define XB_SPIN(cond, bar) do { unsigned _sp = 0; while (cond) { __builtin_amdgcn_s_sleep(1); \
;     if ((++_sp & 255u) == 0u) { if (xb_ld(&(bar)[XB_TMO])) break; if (_sp > XB_SPIN_CAP) { atomicAdd(&(bar)[XB_TMO], 1u); break; } } } } while (0)
; __device__ __forceinline__ void xcd_barrier(const XcdBarrier& b) {
;     ...
;             else XB_SPIN(xb_ld(&bar[XB_TOPGEN]) == tg, bar);
;             __builtin_amdgcn_fence(__ATOMIC_ACQUIRE, "agent");
;             xb_add(&bar[XB_XGEN(b.x)], 1u);
;             asm volatile("s_waitcnt vmcnt(0)" ::: "memory");
;         } else {
;             XB_SPIN(xb_ld(&bar[XB_XGEN(b.x)]) == gen, bar);
.LBB0_366:
	global_load_dword v4, v2, s[16:17] sc1
	s_add_i32 s3, s3, 1
	s_mov_b64 s[24:25], -1
	s_waitcnt vmcnt(0)
	v_cmp_le_u32_e32 vcc, 1, v4
	s_orn2_b64 s[22:23], vcc, exec
	s_branch .LBB0_361

; __device__ __forceinline__ unsigned xb_ld(unsigned* p)              { return __hip_atomic_load(p, __ATOMIC_RELAXED, __HIP_MEMORY_SCOPE_AGENT); }
; __device__ __forceinline__ unsigned xb_add(unsigned* p, unsigned v) { return __hip_atomic_fetch_add(p, v, __ATOMIC_RELAXED, __HIP_MEMORY_SCOPE_AGENT); }
; #define XB_SPIN(cond, bar) do { unsigned _sp = 0; while (cond) { __builtin_amdgcn_s_sleep(1); \
;     if ((++_sp & 255u) == 0u) { if (xb_ld(&(bar)[XB_TMO])) break; if (_sp > XB_SPIN_CAP) { atomicAdd(&(bar)[XB_TMO], 1u); break; } } } } while (0)
; __device__ __forceinline__ void xcd_barrier(const XcdBarrier& b) {
;     ...
;         const unsigned old = xb_add(&bar[XB_XSUB(b.x)], 1u);
;         const unsigned gen = old / nloc;
;         if (old + 1u == (gen + 1u) * nloc) {
;             __builtin_amdgcn_fence(__ATOMIC_RELEASE, "agent");
;             asm volatile("s_waitcnt vmcnt(0)" ::: "memory");
;             const unsigned og = xb_add(&bar[XB_TOP], 1u);
;             const unsigned tg = og / nx;
;             if (og + 1u == (tg + 1u) * nx) xb_add(&bar[XB_TOPGEN], 1u);
;             else XB_SPIN(xb_ld(&bar[XB_TOPGEN]) == tg, bar);
;             __builtin_amdgcn_fence(__ATOMIC_ACQUIRE, "agent");
;             xb_add(&bar[XB_XGEN(b.x)], 1u);
;             asm volatile("s_waitcnt vmcnt(0)" ::: "memory");
;         } else {
;             XB_SPIN(xb_ld(&bar[XB_XGEN(b.x)]) == gen, bar);
;             __builtin_amdgcn_fence(__ATOMIC_ACQUIRE, "agent");
;             asm volatile("s_waitcnt vmcnt(0)" ::: "memory");
;         }
.LBB0_583:
	s_or_b64 exec, exec, s[10:11]
	v_cvt_f32_u32_e32 v6, v4
	s_waitcnt vmcnt(0)
	v_readfirstlane_b32 s3, v5
	v_sub_u32_e32 v5, 0, v4
	v_rcp_iflag_f32_e32 v6, v6
	v_add_u32_e32 v7, s3, v3
	v_mul_f32_e32 v6, 0x4f7ffffe, v6
	v_cvt_u32_f32_e32 v6, v6
	v_mul_lo_u32 v3, v5, v6
	v_mul_hi_u32 v3, v6, v3
	v_add_u32_e32 v3, v6, v3
	v_mul_hi_u32 v3, v7, v3
	v_mul_lo_u32 v5, v3, v4
	v_sub_u32_e32 v5, v7, v5
	v_add_u32_e32 v6, 1, v3
	v_cmp_ge_u32_e32 vcc, v5, v4
	s_nop 1
	v_cndmask_b32_e32 v3, v3, v6, vcc
	v_sub_u32_e32 v6, v5, v4
	v_cndmask_b32_e32 v5, v5, v6, vcc
	v_add_u32_e32 v6, 1, v3
	v_cmp_ge_u32_e32 vcc, v5, v4
	v_add_u32_e32 v5, 1, v7
	s_nop 0
	v_cndmask_b32_e32 v3, v3, v6, vcc
	v_mul_lo_u32 v6, v4, v3
	v_add_u32_e32 v4, v6, v4
	v_cmp_ne_u32_e32 vcc, v5, v4
	s_and_saveexec_b64 s[4:5], vcc
	s_xor_b64 s[8:9], exec, s[4:5]
	s_cbranch_execz .LBB0_597
	s_waitcnt lgkmcnt(0)
	v_mov_b32_e32 v2, 0x7500
	global_load_dword v2, v2, s[94:95] sc1
	s_add_u32 s14, s94, 0x7500
	s_addc_u32 s15, s95, 0
	s_waitcnt vmcnt(0)
	v_cmp_gt_u32_e32 vcc, 2, v2
	s_and_saveexec_b64 s[10:11], vcc
	s_cbranch_execz .LBB0_596
	s_add_u32 s12, s94, 0x4200
	s_addc_u32 s13, s95, 0
	s_mov_b32 s3, 1
	s_mov_b64 s[16:17], 0
	v_mov_b32_e32 v2, 0
	s_branch .LBB0_587

; __device__ __forceinline__ unsigned xb_ld(unsigned* p)              { return __hip_atomic_load(p, __ATOMIC_RELAXED, __HIP_MEMORY_SCOPE_AGENT); }
; __device__ __forceinline__ unsigned xb_add(unsigned* p, unsigned v) { return __hip_atomic_fetch_add(p, v, __ATOMIC_RELAXED, __HIP_MEMORY_SCOPE_AGENT); }
; #define XB_SPIN(cond, bar) do { unsigned _sp = 0; while (cond) { __builtin_amdgcn_s_sleep(1); \
;     if ((++_sp & 255u) == 0u) { if (xb_ld(&(bar)[XB_TMO])) break; if (_sp > XB_SPIN_CAP) { atomicAdd(&(bar)[XB_TMO], 1u); break; } } } } while (0)
; __device__ __forceinline__ void xcd_barrier(const XcdBarrier& b) {
;     ...
;             else XB_SPIN(xb_ld(&bar[XB_TOPGEN]) == tg, bar);
;             __builtin_amdgcn_fence(__ATOMIC_ACQUIRE, "agent");
;             xb_add(&bar[XB_XGEN(b.x)], 1u);
;             asm volatile("s_waitcnt vmcnt(0)" ::: "memory");
;         } else {
;             XB_SPIN(xb_ld(&bar[XB_XGEN(b.x)]) == gen, bar);
.LBB0_591:
	global_load_dword v4, v2, s[14:15] sc1
	s_add_i32 s3, s3, 1
	s_mov_b64 s[22:23], -1
	s_waitcnt vmcnt(0)
	v_cmp_le_u32_e32 vcc, 2, v4
	s_orn2_b64 s[20:21], vcc, exec
	s_branch .LBB0_586

; __device__ __forceinline__ unsigned xb_ld(unsigned* p)              { return __hip_atomic_load(p, __ATOMIC_RELAXED, __HIP_MEMORY_SCOPE_AGENT); }
; __device__ __forceinline__ unsigned xb_add(unsigned* p, unsigned v) { return __hip_atomic_fetch_add(p, v, __ATOMIC_RELAXED, __HIP_MEMORY_SCOPE_AGENT); }
; #define XB_SPIN(cond, bar) do { unsigned _sp = 0; while (cond) { __builtin_amdgcn_s_sleep(1); \
;     if ((++_sp & 255u) == 0u) { if (xb_ld(&(bar)[XB_TMO])) break; if (_sp > XB_SPIN_CAP) { atomicAdd(&(bar)[XB_TMO], 1u); break; } } } } while (0)
; __device__ __forceinline__ void xcd_barrier(const XcdBarrier& b) {
;     ...
;         const unsigned old = xb_add(&bar[XB_XSUB(b.x)], 1u);
;         const unsigned gen = old / nloc;
;         if (old + 1u == (gen + 1u) * nloc) {
;             __builtin_amdgcn_fence(__ATOMIC_RELEASE, "agent");
;             asm volatile("s_waitcnt vmcnt(0)" ::: "memory");
;             const unsigned og = xb_add(&bar[XB_TOP], 1u);
;             const unsigned tg = og / nx;
;             if (og + 1u == (tg + 1u) * nx) xb_add(&bar[XB_TOPGEN], 1u);
;             else XB_SPIN(xb_ld(&bar[XB_TOPGEN]) == tg, bar);
;             __builtin_amdgcn_fence(__ATOMIC_ACQUIRE, "agent");
;             xb_add(&bar[XB_XGEN(b.x)], 1u);
;             asm volatile("s_waitcnt vmcnt(0)" ::: "memory");
;         } else {
;             XB_SPIN(xb_ld(&bar[XB_XGEN(b.x)]) == gen, bar);
;             __builtin_amdgcn_fence(__ATOMIC_ACQUIRE, "agent");
;             asm volatile("s_waitcnt vmcnt(0)" ::: "memory");
;         }
.LBB0_722:
	s_or_b64 exec, exec, s[10:11]
	v_cvt_f32_u32_e32 v6, v4
	s_waitcnt vmcnt(0)
	v_readfirstlane_b32 s2, v5
	v_sub_u32_e32 v5, 0, v4
	v_rcp_iflag_f32_e32 v6, v6
	v_add_u32_e32 v7, s2, v3
	v_mul_f32_e32 v6, 0x4f7ffffe, v6
	v_cvt_u32_f32_e32 v6, v6
	v_mul_lo_u32 v3, v5, v6
	v_mul_hi_u32 v3, v6, v3
	v_add_u32_e32 v3, v6, v3
	v_mul_hi_u32 v3, v7, v3
	v_mul_lo_u32 v5, v3, v4
	v_sub_u32_e32 v5, v7, v5
	v_add_u32_e32 v6, 1, v3
	v_cmp_ge_u32_e32 vcc, v5, v4
	s_nop 1
	v_cndmask_b32_e32 v3, v3, v6, vcc
	v_sub_u32_e32 v6, v5, v4
	v_cndmask_b32_e32 v5, v5, v6, vcc
	v_add_u32_e32 v6, 1, v3
	v_cmp_ge_u32_e32 vcc, v5, v4
	v_add_u32_e32 v5, 1, v7
	s_nop 0
	v_cndmask_b32_e32 v3, v3, v6, vcc
	v_mul_lo_u32 v6, v4, v3
	v_add_u32_e32 v4, v6, v4
	v_cmp_ne_u32_e32 vcc, v5, v4
	s_and_saveexec_b64 s[4:5], vcc
	s_xor_b64 s[8:9], exec, s[4:5]
	s_cbranch_execz .LBB0_736
	s_waitcnt lgkmcnt(0)
	v_mov_b32_e32 v2, 0x7500
	global_load_dword v2, v2, s[94:95] sc1
	s_add_u32 s16, s94, 0x7500
	s_addc_u32 s17, s95, 0
	s_waitcnt vmcnt(0)
	v_cmp_gt_u32_e32 vcc, 3, v2
	s_and_saveexec_b64 s[10:11], vcc
	s_cbranch_execz .LBB0_735
	s_add_u32 s14, s94, 0x4200
	s_addc_u32 s15, s95, 0
	s_mov_b32 s3, 1
	s_mov_b64 s[18:19], 0
	v_mov_b32_e32 v2, 0
	s_branch .LBB0_726

; __device__ __forceinline__ unsigned xb_ld(unsigned* p)              { return __hip_atomic_load(p, __ATOMIC_RELAXED, __HIP_MEMORY_SCOPE_AGENT); }
; __device__ __forceinline__ unsigned xb_add(unsigned* p, unsigned v) { return __hip_atomic_fetch_add(p, v, __ATOMIC_RELAXED, __HIP_MEMORY_SCOPE_AGENT); }
; #define XB_SPIN(cond, bar) do { unsigned _sp = 0; while (cond) { __builtin_amdgcn_s_sleep(1); \
;     if ((++_sp & 255u) == 0u) { if (xb_ld(&(bar)[XB_TMO])) break; if (_sp > XB_SPIN_CAP) { atomicAdd(&(bar)[XB_TMO], 1u); break; } } } } while (0)
; __device__ __forceinline__ void xcd_barrier(const XcdBarrier& b) {
;     ...
;             else XB_SPIN(xb_ld(&bar[XB_TOPGEN]) == tg, bar);
;             __builtin_amdgcn_fence(__ATOMIC_ACQUIRE, "agent");
;             xb_add(&bar[XB_XGEN(b.x)], 1u);
;             asm volatile("s_waitcnt vmcnt(0)" ::: "memory");
;         } else {
;             XB_SPIN(xb_ld(&bar[XB_XGEN(b.x)]) == gen, bar);
.LBB0_730:
	global_load_dword v4, v2, s[16:17] sc1
	s_add_i32 s3, s3, 1
	s_mov_b64 s[24:25], -1
	s_waitcnt vmcnt(0)
	v_cmp_le_u32_e32 vcc, 3, v4
	s_orn2_b64 s[22:23], vcc, exec
	s_branch .LBB0_725
